# grid barrier leaders: wait on the arrival counter like the waiters, own L1 invalidate issued behind the arrival atomic (after the L2 write-back), per-XCD release word no longer bumped
# baseline (speedup 1.0000x reference)
; __device__ __forceinline__ unsigned xb_ld(unsigned* p)              { return __hip_atomic_load(p, __ATOMIC_RELAXED, __HIP_MEMORY_SCOPE_AGENT); }
; __device__ __forceinline__ unsigned xb_add(unsigned* p, unsigned v) { return __hip_atomic_fetch_add(p, v, __ATOMIC_RELAXED, __HIP_MEMORY_SCOPE_AGENT); }
; #define XB_SPIN(cond, bar) do { unsigned _sp = 0; while (cond) { __builtin_amdgcn_s_sleep(1); \
;     if ((++_sp & 255u) == 0u) { if (xb_ld(&(bar)[XB_TMO])) break; if (_sp > XB_SPIN_CAP) { atomicAdd(&(bar)[XB_TMO], 1u); break; } } } } while (0)
; __device__ __forceinline__ void xcd_barrier(const XcdBarrier& b) {
;     ...
;         if (old + 1u == (gen + 1u) * nloc) {
;             __builtin_amdgcn_fence(__ATOMIC_RELEASE, "agent");
;             asm volatile("s_waitcnt vmcnt(0)" ::: "memory");
;             const unsigned og = xb_add(&bar[XB_TOP], 1u);
;             const unsigned tg = og / nx;
;             if (og + 1u == (tg + 1u) * nx) xb_add(&bar[XB_TOPGEN], 1u);
;             else XB_SPIN(xb_ld(&bar[XB_TOPGEN]) == tg, bar);
.LBB0_64:
	s_andn2_saveexec_b64 s[6:7], s[6:7]
	s_cbranch_execz .LBB0_84
	s_mov_b64 s[6:7], exec
	buffer_wbl2 sc1
	s_waitcnt lgkmcnt(0)
	s_waitcnt vmcnt(0)
	v_mbcnt_lo_u32_b32 v1, s6, 0
	v_mbcnt_hi_u32_b32 v1, s7, v1
	v_cmp_eq_u32_e32 vcc, 0, v1
	s_and_saveexec_b64 s[8:9], vcc
	s_cbranch_execz .LBB0_67
	s_bcnt1_i32_b64 s6, s[6:7]
	v_mov_b32_e32 v2, 0xfc3000
	v_mov_b32_e32 v3, s6
	global_atomic_add v2, v2, v3, s[50:51] offset:1024 sc0
	buffer_inv sc1
.LBB0_67:
	s_or_b64 exec, exec, s[8:9]
	v_cvt_f32_u32_e32 v3, v0
	s_waitcnt vmcnt(0)
	v_readfirstlane_b32 s6, v2
	s_add_u32 s8, s50, 0xfc3500
	s_addc_u32 s9, s51, 0
	v_rcp_iflag_f32_e32 v3, v3
	v_add_u32_e32 v1, s6, v1
	v_add_u32_e32 v4, 1, v1
	s_mov_b64 s[10:11], -1
	v_mul_f32_e32 v2, 0x4f7ffffe, v3
	v_cvt_u32_f32_e32 v2, v2
	v_sub_u32_e32 v3, 0, v0
	v_mul_lo_u32 v3, v3, v2
	v_mul_hi_u32 v3, v2, v3
	v_add_u32_e32 v2, v2, v3
	v_mul_hi_u32 v2, v1, v2
	v_mul_lo_u32 v3, v2, v0
	v_sub_u32_e32 v1, v1, v3
	v_add_u32_e32 v5, 1, v2
	v_cmp_ge_u32_e32 vcc, v1, v0
	v_sub_u32_e32 v3, v1, v0
	s_nop 0
	v_cndmask_b32_e32 v2, v2, v5, vcc
	v_cndmask_b32_e32 v1, v1, v3, vcc
	v_add_u32_e32 v3, 1, v2
	v_cmp_ge_u32_e32 vcc, v1, v0
	s_nop 1
	v_cndmask_b32_e32 v2, v2, v3, vcc
	v_mul_lo_u32 v1, v0, v2
	v_add_u32_e32 v0, v1, v0
	v_cmp_ne_u32_e32 vcc, v4, v0
	v_mov_b32_e32 v5, v0
	v_mov_b64_e32 v[0:1], s[8:9]
	s_and_saveexec_b64 s[6:7], vcc
	s_cbranch_execz .LBB0_79
	v_mov_b32_e32 v0, 0
	global_load_dword v1, v0, s[8:9] offset:-256 sc1
	s_mov_b64 s[14:15], 0
	s_waitcnt vmcnt(0)
	v_cmp_lt_u32_e32 vcc, v1, v5
	s_and_saveexec_b64 s[12:13], vcc
	s_cbranch_execz .LBB0_78
	s_add_u32 s10, s50, 0xfc0200
	s_addc_u32 s11, s51, 0
	s_mov_b32 s26, 1
	s_branch .LBB0_71

.LBB0_75:
	global_load_dword v1, v0, s[8:9] offset:-256 sc1
	s_add_i32 s26, s26, 1
	s_mov_b64 s[20:21], -1
	s_waitcnt vmcnt(0)
	v_cmp_ge_u32_e32 vcc, v1, v5
	s_orn2_b64 s[24:25], vcc, exec
	s_branch .LBB0_70

; __device__ __forceinline__ unsigned xb_ld(unsigned* p)              { return __hip_atomic_load(p, __ATOMIC_RELAXED, __HIP_MEMORY_SCOPE_AGENT); }
; __device__ __forceinline__ unsigned xb_add(unsigned* p, unsigned v) { return __hip_atomic_fetch_add(p, v, __ATOMIC_RELAXED, __HIP_MEMORY_SCOPE_AGENT); }
; #define XB_SPIN(cond, bar) do { unsigned _sp = 0; while (cond) { __builtin_amdgcn_s_sleep(1); \
;     if ((++_sp & 255u) == 0u) { if (xb_ld(&(bar)[XB_TMO])) break; if (_sp > XB_SPIN_CAP) { atomicAdd(&(bar)[XB_TMO], 1u); break; } } } } while (0)
; __device__ __forceinline__ void xcd_barrier(const XcdBarrier& b) {
;     ...
;             const unsigned tg = og / nx;
;             if (og + 1u == (tg + 1u) * nx) xb_add(&bar[XB_TOPGEN], 1u);
;             else XB_SPIN(xb_ld(&bar[XB_TOPGEN]) == tg, bar);
.LBB0_393:
	s_or_b64 exec, exec, s[8:9]
	v_cvt_f32_u32_e32 v3, v0
	s_waitcnt vmcnt(0)
	v_readfirstlane_b32 s6, v2
	s_add_u32 s8, s50, 0xfc3500
	s_addc_u32 s9, s51, 0
	v_rcp_iflag_f32_e32 v3, v3
	v_add_u32_e32 v1, s6, v1
	v_add_u32_e32 v4, 1, v1
	s_mov_b64 s[10:11], -1
	v_mul_f32_e32 v2, 0x4f7ffffe, v3
	v_cvt_u32_f32_e32 v2, v2
	v_sub_u32_e32 v3, 0, v0
	v_mul_lo_u32 v3, v3, v2
	v_mul_hi_u32 v3, v2, v3
	v_add_u32_e32 v2, v2, v3
	v_mul_hi_u32 v2, v1, v2
	v_mul_lo_u32 v3, v2, v0
	v_sub_u32_e32 v1, v1, v3
	v_add_u32_e32 v5, 1, v2
	v_cmp_ge_u32_e32 vcc, v1, v0
	v_sub_u32_e32 v3, v1, v0
	s_nop 0
	v_cndmask_b32_e32 v2, v2, v5, vcc
	v_cndmask_b32_e32 v1, v1, v3, vcc
	v_add_u32_e32 v3, 1, v2
	v_cmp_ge_u32_e32 vcc, v1, v0
	s_nop 1
	v_cndmask_b32_e32 v2, v2, v3, vcc
	v_mul_lo_u32 v1, v0, v2
	v_add_u32_e32 v0, v1, v0
	v_cmp_ne_u32_e32 vcc, v4, v0
	v_mov_b32_e32 v5, v0
	v_mov_b64_e32 v[0:1], s[8:9]
	s_and_saveexec_b64 s[6:7], vcc
	s_cbranch_execz .LBB0_405
	v_mov_b32_e32 v0, 0
	global_load_dword v1, v0, s[8:9] offset:-256 sc1
	s_mov_b64 s[14:15], 0
	s_waitcnt vmcnt(0)
	v_cmp_lt_u32_e32 vcc, v1, v5
	s_and_saveexec_b64 s[12:13], vcc
	s_cbranch_execz .LBB0_404
	s_add_u32 s10, s50, 0xfc0200
	s_addc_u32 s11, s51, 0
	s_mov_b32 s28, 1
	s_branch .LBB0_397

.LBB0_401:
	global_load_dword v1, v0, s[8:9] offset:-256 sc1
	s_add_i32 s28, s28, 1
	s_mov_b64 s[22:23], -1
	s_waitcnt vmcnt(0)
	v_cmp_ge_u32_e32 vcc, v1, v5
	s_orn2_b64 s[26:27], vcc, exec
	s_branch .LBB0_396

; __device__ __forceinline__ unsigned xb_ld(unsigned* p)              { return __hip_atomic_load(p, __ATOMIC_RELAXED, __HIP_MEMORY_SCOPE_AGENT); }
; __device__ __forceinline__ unsigned xb_add(unsigned* p, unsigned v) { return __hip_atomic_fetch_add(p, v, __ATOMIC_RELAXED, __HIP_MEMORY_SCOPE_AGENT); }
; #define XB_SPIN(cond, bar) do { unsigned _sp = 0; while (cond) { __builtin_amdgcn_s_sleep(1); \
;     if ((++_sp & 255u) == 0u) { if (xb_ld(&(bar)[XB_TMO])) break; if (_sp > XB_SPIN_CAP) { atomicAdd(&(bar)[XB_TMO], 1u); break; } } } } while (0)
; __device__ __forceinline__ void xcd_barrier(const XcdBarrier& b) {
;     ...
;             const unsigned tg = og / nx;
;             if (og + 1u == (tg + 1u) * nx) xb_add(&bar[XB_TOPGEN], 1u);
;             else XB_SPIN(xb_ld(&bar[XB_TOPGEN]) == tg, bar);
.LBB0_509:
	s_or_b64 exec, exec, s[8:9]
	v_cvt_f32_u32_e32 v3, v0
	s_waitcnt vmcnt(0)
	v_readfirstlane_b32 s6, v2
	s_add_u32 s8, s50, 0xfc3500
	s_addc_u32 s9, s51, 0
	v_rcp_iflag_f32_e32 v3, v3
	v_add_u32_e32 v1, s6, v1
	v_add_u32_e32 v4, 1, v1
	s_mov_b64 s[10:11], -1
	v_mul_f32_e32 v2, 0x4f7ffffe, v3
	v_cvt_u32_f32_e32 v2, v2
	v_sub_u32_e32 v3, 0, v0
	v_mul_lo_u32 v3, v3, v2
	v_mul_hi_u32 v3, v2, v3
	v_add_u32_e32 v2, v2, v3
	v_mul_hi_u32 v2, v1, v2
	v_mul_lo_u32 v3, v2, v0
	v_sub_u32_e32 v1, v1, v3
	v_add_u32_e32 v5, 1, v2
	v_cmp_ge_u32_e32 vcc, v1, v0
	v_sub_u32_e32 v3, v1, v0
	s_nop 0
	v_cndmask_b32_e32 v2, v2, v5, vcc
	v_cndmask_b32_e32 v1, v1, v3, vcc
	v_add_u32_e32 v3, 1, v2
	v_cmp_ge_u32_e32 vcc, v1, v0
	s_nop 1
	v_cndmask_b32_e32 v2, v2, v3, vcc
	v_mul_lo_u32 v1, v0, v2
	v_add_u32_e32 v0, v1, v0
	v_cmp_ne_u32_e32 vcc, v4, v0
	v_mov_b32_e32 v5, v0
	v_mov_b64_e32 v[0:1], s[8:9]
	s_and_saveexec_b64 s[6:7], vcc
	s_cbranch_execz .LBB0_521
	v_mov_b32_e32 v0, 0
	global_load_dword v1, v0, s[8:9] offset:-256 sc1
	s_mov_b64 s[14:15], 0
	s_waitcnt vmcnt(0)
	v_cmp_lt_u32_e32 vcc, v1, v5
	s_and_saveexec_b64 s[12:13], vcc
	s_cbranch_execz .LBB0_520
	s_add_u32 s10, s50, 0xfc0200
	s_addc_u32 s11, s51, 0
	s_mov_b32 s30, 1
	s_branch .LBB0_513

.LBB0_517:
	global_load_dword v1, v0, s[8:9] offset:-256 sc1
	s_add_i32 s30, s30, 1
	s_mov_b64 s[24:25], -1
	s_waitcnt vmcnt(0)
	v_cmp_ge_u32_e32 vcc, v1, v5
	s_orn2_b64 s[28:29], vcc, exec
	s_branch .LBB0_512

; __device__ __forceinline__ unsigned xb_ld(unsigned* p)              { return __hip_atomic_load(p, __ATOMIC_RELAXED, __HIP_MEMORY_SCOPE_AGENT); }
; __device__ __forceinline__ unsigned xb_add(unsigned* p, unsigned v) { return __hip_atomic_fetch_add(p, v, __ATOMIC_RELAXED, __HIP_MEMORY_SCOPE_AGENT); }
; #define XB_SPIN(cond, bar) do { unsigned _sp = 0; while (cond) { __builtin_amdgcn_s_sleep(1); \
;     if ((++_sp & 255u) == 0u) { if (xb_ld(&(bar)[XB_TMO])) break; if (_sp > XB_SPIN_CAP) { atomicAdd(&(bar)[XB_TMO], 1u); break; } } } } while (0)
; __device__ __forceinline__ void xcd_barrier(const XcdBarrier& b) {
;     ...
;         if (old + 1u == (gen + 1u) * nloc) {
;             __builtin_amdgcn_fence(__ATOMIC_RELEASE, "agent");
;             asm volatile("s_waitcnt vmcnt(0)" ::: "memory");
;             const unsigned og = xb_add(&bar[XB_TOP], 1u);
;             const unsigned tg = og / nx;
;             if (og + 1u == (tg + 1u) * nx) xb_add(&bar[XB_TOPGEN], 1u);
;             else XB_SPIN(xb_ld(&bar[XB_TOPGEN]) == tg, bar);
.LBB0_600:
	s_andn2_saveexec_b64 s[8:9], s[8:9]
	s_cbranch_execz .LBB0_620
	s_mov_b64 s[8:9], exec
	buffer_wbl2 sc1
	s_waitcnt lgkmcnt(0)
	s_waitcnt vmcnt(0)
	v_mbcnt_lo_u32_b32 v1, s8, 0
	v_mbcnt_hi_u32_b32 v1, s9, v1
	v_cmp_eq_u32_e32 vcc, 0, v1
	s_and_saveexec_b64 s[14:15], vcc
	s_cbranch_execz .LBB0_603
	s_bcnt1_i32_b64 s8, s[8:9]
	v_mov_b32_e32 v2, 0xfc3000
	v_mov_b32_e32 v3, s8
	global_atomic_add v2, v2, v3, s[50:51] offset:1024 sc0
	buffer_inv sc1
.LBB0_603:
	s_or_b64 exec, exec, s[14:15]
	v_cvt_f32_u32_e32 v3, v0
	s_waitcnt vmcnt(0)
	v_readfirstlane_b32 s8, v2
	s_add_u32 s14, s50, 0xfc3500
	s_addc_u32 s15, s51, 0
	v_rcp_iflag_f32_e32 v3, v3
	v_add_u32_e32 v1, s8, v1
	v_add_u32_e32 v4, 1, v1
	s_mov_b64 s[16:17], -1
	v_mul_f32_e32 v2, 0x4f7ffffe, v3
	v_cvt_u32_f32_e32 v2, v2
	v_sub_u32_e32 v3, 0, v0
	v_mul_lo_u32 v3, v3, v2
	v_mul_hi_u32 v3, v2, v3
	v_add_u32_e32 v2, v2, v3
	v_mul_hi_u32 v2, v1, v2
	v_mul_lo_u32 v3, v2, v0
	v_sub_u32_e32 v1, v1, v3
	v_add_u32_e32 v5, 1, v2
	v_cmp_ge_u32_e32 vcc, v1, v0
	v_sub_u32_e32 v3, v1, v0
	s_nop 0
	v_cndmask_b32_e32 v2, v2, v5, vcc
	v_cndmask_b32_e32 v1, v1, v3, vcc
	v_add_u32_e32 v3, 1, v2
	v_cmp_ge_u32_e32 vcc, v1, v0
	s_nop 1
	v_cndmask_b32_e32 v2, v2, v3, vcc
	v_mul_lo_u32 v1, v0, v2
	v_add_u32_e32 v0, v1, v0
	v_cmp_ne_u32_e32 vcc, v4, v0
	v_mov_b32_e32 v5, v0
	v_mov_b64_e32 v[0:1], s[14:15]
	s_and_saveexec_b64 s[8:9], vcc
	s_cbranch_execz .LBB0_615
	v_mov_b32_e32 v0, 0
	global_load_dword v1, v0, s[14:15] offset:-256 sc1
	s_mov_b64 s[26:27], 0
	s_waitcnt vmcnt(0)
	v_cmp_lt_u32_e32 vcc, v1, v5
	s_and_saveexec_b64 s[24:25], vcc
	s_cbranch_execz .LBB0_614
	s_add_u32 s16, s50, 0xfc0200
	s_addc_u32 s17, s51, 0
	s_mov_b32 s33, 1
	s_branch .LBB0_607

.LBB0_611:
	global_load_dword v1, v0, s[14:15] offset:-256 sc1
	s_add_i32 s33, s33, 1
	s_mov_b64 s[30:31], -1
	s_waitcnt vmcnt(0)
	v_cmp_ge_u32_e32 vcc, v1, v5
	s_orn2_b64 s[36:37], vcc, exec
	s_branch .LBB0_606

; __device__ __forceinline__ unsigned xb_ld(unsigned* p)              { return __hip_atomic_load(p, __ATOMIC_RELAXED, __HIP_MEMORY_SCOPE_AGENT); }
; __device__ __forceinline__ unsigned xb_add(unsigned* p, unsigned v) { return __hip_atomic_fetch_add(p, v, __ATOMIC_RELAXED, __HIP_MEMORY_SCOPE_AGENT); }
; #define XB_SPIN(cond, bar) do { unsigned _sp = 0; while (cond) { __builtin_amdgcn_s_sleep(1); \
;     if ((++_sp & 255u) == 0u) { if (xb_ld(&(bar)[XB_TMO])) break; if (_sp > XB_SPIN_CAP) { atomicAdd(&(bar)[XB_TMO], 1u); break; } } } } while (0)
; __device__ __forceinline__ void xcd_barrier(const XcdBarrier& b) {
;     ...
;         if (old + 1u == (gen + 1u) * nloc) {
;             __builtin_amdgcn_fence(__ATOMIC_RELEASE, "agent");
;             asm volatile("s_waitcnt vmcnt(0)" ::: "memory");
;             const unsigned og = xb_add(&bar[XB_TOP], 1u);
;             const unsigned tg = og / nx;
;             if (og + 1u == (tg + 1u) * nx) xb_add(&bar[XB_TOPGEN], 1u);
;             else XB_SPIN(xb_ld(&bar[XB_TOPGEN]) == tg, bar);
.LBB0_676:
	s_andn2_saveexec_b64 s[8:9], s[8:9]
	s_cbranch_execz .LBB0_696
	s_mov_b64 s[8:9], exec
	buffer_wbl2 sc1
	s_waitcnt lgkmcnt(0)
	s_waitcnt vmcnt(0)
	v_mbcnt_lo_u32_b32 v1, s8, 0
	v_mbcnt_hi_u32_b32 v1, s9, v1
	v_cmp_eq_u32_e32 vcc, 0, v1
	s_and_saveexec_b64 s[14:15], vcc
	s_cbranch_execz .LBB0_679
	s_bcnt1_i32_b64 s3, s[8:9]
	v_mov_b32_e32 v2, 0xfc3000
	v_mov_b32_e32 v3, s3
	global_atomic_add v2, v2, v3, s[50:51] offset:1024 sc0
	buffer_inv sc1
.LBB0_679:
	s_or_b64 exec, exec, s[14:15]
	v_cvt_f32_u32_e32 v3, v0
	s_waitcnt vmcnt(0)
	v_readfirstlane_b32 s3, v2
	s_add_u32 s14, s50, 0xfc3500
	s_addc_u32 s15, s51, 0
	v_rcp_iflag_f32_e32 v3, v3
	v_add_u32_e32 v1, s3, v1
	v_add_u32_e32 v4, 1, v1
	s_mov_b64 s[16:17], -1
	v_mul_f32_e32 v2, 0x4f7ffffe, v3
	v_cvt_u32_f32_e32 v2, v2
	v_sub_u32_e32 v3, 0, v0
	v_mul_lo_u32 v3, v3, v2
	v_mul_hi_u32 v3, v2, v3
	v_add_u32_e32 v2, v2, v3
	v_mul_hi_u32 v2, v1, v2
	v_mul_lo_u32 v3, v2, v0
	v_sub_u32_e32 v1, v1, v3
	v_add_u32_e32 v5, 1, v2
	v_cmp_ge_u32_e32 vcc, v1, v0
	v_sub_u32_e32 v3, v1, v0
	s_nop 0
	v_cndmask_b32_e32 v2, v2, v5, vcc
	v_cndmask_b32_e32 v1, v1, v3, vcc
	v_add_u32_e32 v3, 1, v2
	v_cmp_ge_u32_e32 vcc, v1, v0
	s_nop 1
	v_cndmask_b32_e32 v2, v2, v3, vcc
	v_mul_lo_u32 v1, v0, v2
	v_add_u32_e32 v0, v1, v0
	v_cmp_ne_u32_e32 vcc, v4, v0
	v_mov_b32_e32 v5, v0
	v_mov_b64_e32 v[0:1], s[14:15]
	s_and_saveexec_b64 s[8:9], vcc
	s_cbranch_execz .LBB0_691
	v_mov_b32_e32 v0, 0
	global_load_dword v1, v0, s[14:15] offset:-256 sc1
	s_mov_b64 s[22:23], 0
	s_waitcnt vmcnt(0)
	v_cmp_lt_u32_e32 vcc, v1, v5
	s_and_saveexec_b64 s[18:19], vcc
	s_cbranch_execz .LBB0_690
	s_add_u32 s16, s50, 0xfc0200
	s_addc_u32 s17, s51, 0
	s_mov_b32 s3, 1
	s_branch .LBB0_683

.LBB0_687:
	global_load_dword v1, v0, s[14:15] offset:-256 sc1
	s_add_i32 s3, s3, 1
	s_mov_b64 s[26:27], -1
	s_waitcnt vmcnt(0)
	v_cmp_ge_u32_e32 vcc, v1, v5
	s_orn2_b64 s[30:31], vcc, exec
	s_branch .LBB0_682
